# attention PV specialised per V-half (no P-fragment cndmask); stage C: parallel prefix max, straight-line Q/K/CT/V staging loads
# speedup vs baseline: 1.0252x; 1.0125x over previous
.LBB0_738:
	s_cmp_lg_u64 s[2:3], 0
	s_cbranch_scc0 .Lcnd0_vh1
	ds_read_b64_tr_b16 v[180:181], v158 offset:0
	ds_read_b64_tr_b16 v[182:183], v158 offset:0x800
	ds_read_b64_tr_b16 v[184:185], v158 offset:0x1000
	ds_read_b64_tr_b16 v[186:187], v158 offset:0x1800
	ds_read_b64_tr_b16 v[188:189], v158 offset:0x2000
	ds_read_b64_tr_b16 v[190:191], v158 offset:0x2800
	ds_read_b64_tr_b16 v[192:193], v158 offset:0x3000
	ds_read_b64_tr_b16 v[194:195], v158 offset:0x3800
	s_waitcnt lgkmcnt(0)
	s_waitcnt lgkmcnt(0)
	v_max_f32_e32 v168, v166, v166
	v_max_f32_e32 v169, v164, v164
	v_max_f32_e32 v168, v169, v168
	s_nop 1
	v_mfma_f32_32x32x16_bf16 v[48:63], v[112:115], v[180:183], v[48:63]
	ds_read_b64_tr_b16 v[180:181], v158 offset:0x200
	ds_read_b64_tr_b16 v[182:183], v158 offset:0xa00
	v_mfma_f32_32x32x16_bf16 v[48:63], v[116:119], v[184:187], v[48:63]
	ds_read_b64_tr_b16 v[184:185], v158 offset:0x1200
	ds_read_b64_tr_b16 v[186:187], v158 offset:0x1a00
	v_mfma_f32_32x32x16_bf16 v[48:63], v[120:123], v[188:191], v[48:63]
	ds_read_b64_tr_b16 v[188:189], v158 offset:0x2200
	ds_read_b64_tr_b16 v[190:191], v158 offset:0x2a00
	v_mfma_f32_32x32x16_bf16 v[48:63], v[124:127], v[192:195], v[48:63]
	ds_read_b64_tr_b16 v[192:193], v158 offset:0x3200
	ds_read_b64_tr_b16 v[194:195], v158 offset:0x3a00
	s_waitcnt lgkmcnt(0)
	v_mfma_f32_32x32x16_bf16 v[32:47], v[112:115], v[180:183], v[32:47]
	ds_read_b64_tr_b16 v[180:181], v158 offset:0x400
	ds_read_b64_tr_b16 v[182:183], v158 offset:0xc00
	v_mfma_f32_32x32x16_bf16 v[32:47], v[116:119], v[184:187], v[32:47]
	ds_read_b64_tr_b16 v[184:185], v158 offset:0x1400
	ds_read_b64_tr_b16 v[186:187], v158 offset:0x1c00
	v_mfma_f32_32x32x16_bf16 v[32:47], v[120:123], v[188:191], v[32:47]
	ds_read_b64_tr_b16 v[188:189], v158 offset:0x2400
	ds_read_b64_tr_b16 v[190:191], v158 offset:0x2c00
	v_mfma_f32_32x32x16_bf16 v[32:47], v[124:127], v[192:195], v[32:47]
	ds_read_b64_tr_b16 v[192:193], v158 offset:0x3400
	ds_read_b64_tr_b16 v[194:195], v158 offset:0x3c00
	s_waitcnt lgkmcnt(0)
	v_mfma_f32_32x32x16_bf16 v[16:31], v[112:115], v[180:183], v[16:31]
	ds_read_b64_tr_b16 v[180:181], v158 offset:0x600
	ds_read_b64_tr_b16 v[182:183], v158 offset:0xe00
	v_mfma_f32_32x32x16_bf16 v[16:31], v[116:119], v[184:187], v[16:31]
	ds_read_b64_tr_b16 v[184:185], v158 offset:0x1600
	ds_read_b64_tr_b16 v[186:187], v158 offset:0x1e00
	v_mfma_f32_32x32x16_bf16 v[16:31], v[120:123], v[188:191], v[16:31]
	ds_read_b64_tr_b16 v[188:189], v158 offset:0x2600
	ds_read_b64_tr_b16 v[190:191], v158 offset:0x2e00
	v_mfma_f32_32x32x16_bf16 v[16:31], v[124:127], v[192:195], v[16:31]
	ds_read_b64_tr_b16 v[192:193], v158 offset:0x3600
	ds_read_b64_tr_b16 v[194:195], v158 offset:0x3e00
	s_waitcnt lgkmcnt(0)
	v_mfma_f32_32x32x16_bf16 v[0:15], v[112:115], v[180:183], v[0:15]
	v_sub_f32_e32 v169, v168, v165
	v_mul_f32_e32 v169, 0x3db504f3, v169
	v_cmp_ge_f32_e32 vcc, s88, v169
	s_cmp_eq_u64 vcc, exec
	v_mfma_f32_32x32x16_bf16 v[0:15], v[116:119], v[184:187], v[0:15]
	v_mfma_f32_32x32x16_bf16 v[0:15], v[120:123], v[188:191], v[0:15]
	v_mfma_f32_32x32x16_bf16 v[0:15], v[124:127], v[192:195], v[0:15]
	s_cbranch_scc1 .LBB0_742
	s_branch .Lcnd0_rare
.Lcnd0_vh1:
	ds_read_b64_tr_b16 v[180:181], v158 offset:0
	ds_read_b64_tr_b16 v[182:183], v158 offset:0x800
	ds_read_b64_tr_b16 v[184:185], v158 offset:0x1000
	ds_read_b64_tr_b16 v[186:187], v158 offset:0x1800
	ds_read_b64_tr_b16 v[188:189], v158 offset:0x2000
	ds_read_b64_tr_b16 v[190:191], v158 offset:0x2800
	ds_read_b64_tr_b16 v[192:193], v158 offset:0x3000
	ds_read_b64_tr_b16 v[194:195], v158 offset:0x3800
	s_waitcnt lgkmcnt(0)
	s_waitcnt lgkmcnt(0)
	v_max_f32_e32 v168, v166, v166
	v_max_f32_e32 v169, v164, v164
	v_max_f32_e32 v168, v169, v168
	s_nop 1
	v_mfma_f32_32x32x16_bf16 v[48:63], v[120:123], v[180:183], v[48:63]
	ds_read_b64_tr_b16 v[180:181], v158 offset:0x200
	ds_read_b64_tr_b16 v[182:183], v158 offset:0xa00
	v_mfma_f32_32x32x16_bf16 v[48:63], v[124:127], v[184:187], v[48:63]
	ds_read_b64_tr_b16 v[184:185], v158 offset:0x1200
	ds_read_b64_tr_b16 v[186:187], v158 offset:0x1a00
	v_mfma_f32_32x32x16_bf16 v[48:63], v[112:115], v[188:191], v[48:63]
	ds_read_b64_tr_b16 v[188:189], v158 offset:0x2200
	ds_read_b64_tr_b16 v[190:191], v158 offset:0x2a00
	v_mfma_f32_32x32x16_bf16 v[48:63], v[116:119], v[192:195], v[48:63]
	ds_read_b64_tr_b16 v[192:193], v158 offset:0x3200
	ds_read_b64_tr_b16 v[194:195], v158 offset:0x3a00
	s_waitcnt lgkmcnt(0)
	v_mfma_f32_32x32x16_bf16 v[32:47], v[120:123], v[180:183], v[32:47]
	ds_read_b64_tr_b16 v[180:181], v158 offset:0x400
	ds_read_b64_tr_b16 v[182:183], v158 offset:0xc00
	v_mfma_f32_32x32x16_bf16 v[32:47], v[124:127], v[184:187], v[32:47]
	ds_read_b64_tr_b16 v[184:185], v158 offset:0x1400
	ds_read_b64_tr_b16 v[186:187], v158 offset:0x1c00
	v_mfma_f32_32x32x16_bf16 v[32:47], v[112:115], v[188:191], v[32:47]
	ds_read_b64_tr_b16 v[188:189], v158 offset:0x2400
	ds_read_b64_tr_b16 v[190:191], v158 offset:0x2c00
	v_mfma_f32_32x32x16_bf16 v[32:47], v[116:119], v[192:195], v[32:47]
	ds_read_b64_tr_b16 v[192:193], v158 offset:0x3400
	ds_read_b64_tr_b16 v[194:195], v158 offset:0x3c00
	s_waitcnt lgkmcnt(0)
	v_mfma_f32_32x32x16_bf16 v[16:31], v[120:123], v[180:183], v[16:31]
	ds_read_b64_tr_b16 v[180:181], v158 offset:0x600
	ds_read_b64_tr_b16 v[182:183], v158 offset:0xe00
	v_mfma_f32_32x32x16_bf16 v[16:31], v[124:127], v[184:187], v[16:31]
	ds_read_b64_tr_b16 v[184:185], v158 offset:0x1600
	ds_read_b64_tr_b16 v[186:187], v158 offset:0x1e00
	v_mfma_f32_32x32x16_bf16 v[16:31], v[112:115], v[188:191], v[16:31]
	ds_read_b64_tr_b16 v[188:189], v158 offset:0x2600
	ds_read_b64_tr_b16 v[190:191], v158 offset:0x2e00
	v_mfma_f32_32x32x16_bf16 v[16:31], v[116:119], v[192:195], v[16:31]
	ds_read_b64_tr_b16 v[192:193], v158 offset:0x3600
	ds_read_b64_tr_b16 v[194:195], v158 offset:0x3e00
	s_waitcnt lgkmcnt(0)
	v_mfma_f32_32x32x16_bf16 v[0:15], v[120:123], v[180:183], v[0:15]
	v_sub_f32_e32 v169, v168, v165
	v_mul_f32_e32 v169, 0x3db504f3, v169
	v_cmp_ge_f32_e32 vcc, s88, v169
	s_cmp_eq_u64 vcc, exec
	v_mfma_f32_32x32x16_bf16 v[0:15], v[124:127], v[184:187], v[0:15]
	v_mfma_f32_32x32x16_bf16 v[0:15], v[112:115], v[188:191], v[0:15]
	v_mfma_f32_32x32x16_bf16 v[0:15], v[116:119], v[192:195], v[0:15]
	s_cbranch_scc1 .LBB0_742
.Lcnd0_rare:
	v_mov_b32_e32 v120, v168
	v_max_f32_e32 v120, v120, v120
	v_max_f32_e32 v121, v165, v165
	v_max_f32_e32 v166, v121, v120
	v_sub_f32_e32 v120, v165, v166
	v_mul_f32_e32 v120, 0x3e0293ee, v120
	v_exp_f32_e32 v120, v120
	s_and_saveexec_b64 s[54:55], s[4:5]
	ds_write_b32 v159, v120
	s_or_b64 exec, exec, s[54:55]
	s_waitcnt lgkmcnt(0)
	v_mul_f32_e32 v155, v155, v120
	ds_read_b128 v[120:123], v161
	ds_read_b128 v[124:127], v161 offset:32
	ds_read_b128 v[168:171], v161 offset:64
	ds_read_b128 v[172:175], v161 offset:96
	s_waitcnt lgkmcnt(0)
	v_pk_mul_f32 v[50:51], v[50:51], v[122:123]
	v_pk_mul_f32 v[54:55], v[54:55], v[126:127]
	v_pk_mul_f32 v[58:59], v[58:59], v[170:171]
	v_pk_mul_f32 v[62:63], v[62:63], v[174:175]
	v_pk_mul_f32 v[60:61], v[60:61], v[172:173]
	v_pk_mul_f32 v[56:57], v[56:57], v[168:169]
	v_pk_mul_f32 v[52:53], v[52:53], v[124:125]
	v_pk_mul_f32 v[48:49], v[48:49], v[120:121]
	v_pk_mul_f32 v[46:47], v[46:47], v[174:175]
	v_pk_mul_f32 v[42:43], v[42:43], v[170:171]
	v_pk_mul_f32 v[38:39], v[38:39], v[126:127]
	v_pk_mul_f32 v[34:35], v[34:35], v[122:123]
	v_pk_mul_f32 v[44:45], v[44:45], v[172:173]
	v_pk_mul_f32 v[40:41], v[40:41], v[168:169]
	v_pk_mul_f32 v[36:37], v[36:37], v[124:125]
	v_pk_mul_f32 v[32:33], v[32:33], v[120:121]
	v_pk_mul_f32 v[30:31], v[30:31], v[174:175]
	v_pk_mul_f32 v[26:27], v[26:27], v[170:171]
	v_pk_mul_f32 v[22:23], v[22:23], v[126:127]
	v_pk_mul_f32 v[18:19], v[18:19], v[122:123]
	v_pk_mul_f32 v[28:29], v[28:29], v[172:173]
	v_pk_mul_f32 v[24:25], v[24:25], v[168:169]
	v_pk_mul_f32 v[20:21], v[20:21], v[124:125]
	v_pk_mul_f32 v[16:17], v[16:17], v[120:121]
	v_pk_mul_f32 v[14:15], v[14:15], v[174:175]
	v_pk_mul_f32 v[10:11], v[10:11], v[170:171]
	v_pk_mul_f32 v[6:7], v[6:7], v[126:127]
	v_pk_mul_f32 v[2:3], v[2:3], v[122:123]
	v_pk_mul_f32 v[12:13], v[12:13], v[172:173]
	v_pk_mul_f32 v[8:9], v[8:9], v[168:169]
	v_pk_mul_f32 v[4:5], v[4:5], v[124:125]
	v_pk_mul_f32 v[0:1], v[0:1], v[120:121]
	s_andn2_b64 vcc, exec, s[52:53]
	s_cbranch_vccz .LBB0_743
	s_branch .LBB0_748

.LBB0_752:
	s_cmp_lg_u64 s[2:3], 0
	s_cbranch_scc0 .Lcnd1_vh1
	ds_read_b64_tr_b16 v[180:181], v158 offset:0x8000
	ds_read_b64_tr_b16 v[182:183], v158 offset:0x8800
	ds_read_b64_tr_b16 v[184:185], v158 offset:0x9000
	ds_read_b64_tr_b16 v[186:187], v158 offset:0x9800
	ds_read_b64_tr_b16 v[188:189], v158 offset:0xa000
	ds_read_b64_tr_b16 v[190:191], v158 offset:0xa800
	ds_read_b64_tr_b16 v[192:193], v158 offset:0xb000
	ds_read_b64_tr_b16 v[194:195], v158 offset:0xb800
	s_waitcnt lgkmcnt(0)
	s_waitcnt lgkmcnt(0)
	v_max_f32_e32 v168, v128, v128
	v_max_f32_e32 v169, v164, v164
	v_max_f32_e32 v168, v169, v168
	s_nop 1
	v_mfma_f32_32x32x16_bf16 v[48:63], v[112:115], v[180:183], v[48:63]
	ds_read_b64_tr_b16 v[180:181], v158 offset:0x8200
	ds_read_b64_tr_b16 v[182:183], v158 offset:0x8a00
	v_mfma_f32_32x32x16_bf16 v[48:63], v[116:119], v[184:187], v[48:63]
	ds_read_b64_tr_b16 v[184:185], v158 offset:0x9200
	ds_read_b64_tr_b16 v[186:187], v158 offset:0x9a00
	v_mfma_f32_32x32x16_bf16 v[48:63], v[120:123], v[188:191], v[48:63]
	ds_read_b64_tr_b16 v[188:189], v158 offset:0xa200
	ds_read_b64_tr_b16 v[190:191], v158 offset:0xaa00
	v_mfma_f32_32x32x16_bf16 v[48:63], v[124:127], v[192:195], v[48:63]
	ds_read_b64_tr_b16 v[192:193], v158 offset:0xb200
	ds_read_b64_tr_b16 v[194:195], v158 offset:0xba00
	s_waitcnt lgkmcnt(0)
	v_mfma_f32_32x32x16_bf16 v[32:47], v[112:115], v[180:183], v[32:47]
	ds_read_b64_tr_b16 v[180:181], v158 offset:0x8400
	ds_read_b64_tr_b16 v[182:183], v158 offset:0x8c00
	v_mfma_f32_32x32x16_bf16 v[32:47], v[116:119], v[184:187], v[32:47]
	ds_read_b64_tr_b16 v[184:185], v158 offset:0x9400
	ds_read_b64_tr_b16 v[186:187], v158 offset:0x9c00
	v_mfma_f32_32x32x16_bf16 v[32:47], v[120:123], v[188:191], v[32:47]
	ds_read_b64_tr_b16 v[188:189], v158 offset:0xa400
	ds_read_b64_tr_b16 v[190:191], v158 offset:0xac00
	v_mfma_f32_32x32x16_bf16 v[32:47], v[124:127], v[192:195], v[32:47]
	ds_read_b64_tr_b16 v[192:193], v158 offset:0xb400
	ds_read_b64_tr_b16 v[194:195], v158 offset:0xbc00
	s_waitcnt lgkmcnt(0)
	v_mfma_f32_32x32x16_bf16 v[16:31], v[112:115], v[180:183], v[16:31]
	ds_read_b64_tr_b16 v[180:181], v158 offset:0x8600
	ds_read_b64_tr_b16 v[182:183], v158 offset:0x8e00
	v_mfma_f32_32x32x16_bf16 v[16:31], v[116:119], v[184:187], v[16:31]
	ds_read_b64_tr_b16 v[184:185], v158 offset:0x9600
	ds_read_b64_tr_b16 v[186:187], v158 offset:0x9e00
	v_mfma_f32_32x32x16_bf16 v[16:31], v[120:123], v[188:191], v[16:31]
	ds_read_b64_tr_b16 v[188:189], v158 offset:0xa600
	ds_read_b64_tr_b16 v[190:191], v158 offset:0xae00
	v_mfma_f32_32x32x16_bf16 v[16:31], v[124:127], v[192:195], v[16:31]
	ds_read_b64_tr_b16 v[192:193], v158 offset:0xb600
	ds_read_b64_tr_b16 v[194:195], v158 offset:0xbe00
	s_waitcnt lgkmcnt(0)
	v_mfma_f32_32x32x16_bf16 v[0:15], v[112:115], v[180:183], v[0:15]
	v_sub_f32_e32 v169, v168, v166
	v_mul_f32_e32 v169, 0x3db504f3, v169
	v_cmp_ge_f32_e32 vcc, s88, v169
	s_cmp_eq_u64 vcc, exec
	v_mfma_f32_32x32x16_bf16 v[0:15], v[116:119], v[184:187], v[0:15]
	v_mfma_f32_32x32x16_bf16 v[0:15], v[120:123], v[188:191], v[0:15]
	v_mfma_f32_32x32x16_bf16 v[0:15], v[124:127], v[192:195], v[0:15]
	s_cbranch_scc1 .LBB0_756
	s_branch .Lcnd1_rare
.Lcnd1_vh1:
	ds_read_b64_tr_b16 v[180:181], v158 offset:0x8000
	ds_read_b64_tr_b16 v[182:183], v158 offset:0x8800
	ds_read_b64_tr_b16 v[184:185], v158 offset:0x9000
	ds_read_b64_tr_b16 v[186:187], v158 offset:0x9800
	ds_read_b64_tr_b16 v[188:189], v158 offset:0xa000
	ds_read_b64_tr_b16 v[190:191], v158 offset:0xa800
	ds_read_b64_tr_b16 v[192:193], v158 offset:0xb000
	ds_read_b64_tr_b16 v[194:195], v158 offset:0xb800
	s_waitcnt lgkmcnt(0)
	s_waitcnt lgkmcnt(0)
	v_max_f32_e32 v168, v128, v128
	v_max_f32_e32 v169, v164, v164
	v_max_f32_e32 v168, v169, v168
	s_nop 1
	v_mfma_f32_32x32x16_bf16 v[48:63], v[120:123], v[180:183], v[48:63]
	ds_read_b64_tr_b16 v[180:181], v158 offset:0x8200
	ds_read_b64_tr_b16 v[182:183], v158 offset:0x8a00
	v_mfma_f32_32x32x16_bf16 v[48:63], v[124:127], v[184:187], v[48:63]
	ds_read_b64_tr_b16 v[184:185], v158 offset:0x9200
	ds_read_b64_tr_b16 v[186:187], v158 offset:0x9a00
	v_mfma_f32_32x32x16_bf16 v[48:63], v[112:115], v[188:191], v[48:63]
	ds_read_b64_tr_b16 v[188:189], v158 offset:0xa200
	ds_read_b64_tr_b16 v[190:191], v158 offset:0xaa00
	v_mfma_f32_32x32x16_bf16 v[48:63], v[116:119], v[192:195], v[48:63]
	ds_read_b64_tr_b16 v[192:193], v158 offset:0xb200
	ds_read_b64_tr_b16 v[194:195], v158 offset:0xba00
	s_waitcnt lgkmcnt(0)
	v_mfma_f32_32x32x16_bf16 v[32:47], v[120:123], v[180:183], v[32:47]
	ds_read_b64_tr_b16 v[180:181], v158 offset:0x8400
	ds_read_b64_tr_b16 v[182:183], v158 offset:0x8c00
	v_mfma_f32_32x32x16_bf16 v[32:47], v[124:127], v[184:187], v[32:47]
	ds_read_b64_tr_b16 v[184:185], v158 offset:0x9400
	ds_read_b64_tr_b16 v[186:187], v158 offset:0x9c00
	v_mfma_f32_32x32x16_bf16 v[32:47], v[112:115], v[188:191], v[32:47]
	ds_read_b64_tr_b16 v[188:189], v158 offset:0xa400
	ds_read_b64_tr_b16 v[190:191], v158 offset:0xac00
	v_mfma_f32_32x32x16_bf16 v[32:47], v[116:119], v[192:195], v[32:47]
	ds_read_b64_tr_b16 v[192:193], v158 offset:0xb400
	ds_read_b64_tr_b16 v[194:195], v158 offset:0xbc00
	s_waitcnt lgkmcnt(0)
	v_mfma_f32_32x32x16_bf16 v[16:31], v[120:123], v[180:183], v[16:31]
	ds_read_b64_tr_b16 v[180:181], v158 offset:0x8600
	ds_read_b64_tr_b16 v[182:183], v158 offset:0x8e00
	v_mfma_f32_32x32x16_bf16 v[16:31], v[124:127], v[184:187], v[16:31]
	ds_read_b64_tr_b16 v[184:185], v158 offset:0x9600
	ds_read_b64_tr_b16 v[186:187], v158 offset:0x9e00
	v_mfma_f32_32x32x16_bf16 v[16:31], v[112:115], v[188:191], v[16:31]
	ds_read_b64_tr_b16 v[188:189], v158 offset:0xa600
	ds_read_b64_tr_b16 v[190:191], v158 offset:0xae00
	v_mfma_f32_32x32x16_bf16 v[16:31], v[116:119], v[192:195], v[16:31]
	ds_read_b64_tr_b16 v[192:193], v158 offset:0xb600
	ds_read_b64_tr_b16 v[194:195], v158 offset:0xbe00
	s_waitcnt lgkmcnt(0)
	v_mfma_f32_32x32x16_bf16 v[0:15], v[120:123], v[180:183], v[0:15]
	v_sub_f32_e32 v169, v168, v166
	v_mul_f32_e32 v169, 0x3db504f3, v169
	v_cmp_ge_f32_e32 vcc, s88, v169
	s_cmp_eq_u64 vcc, exec
	v_mfma_f32_32x32x16_bf16 v[0:15], v[124:127], v[184:187], v[0:15]
	v_mfma_f32_32x32x16_bf16 v[0:15], v[112:115], v[188:191], v[0:15]
	v_mfma_f32_32x32x16_bf16 v[0:15], v[116:119], v[192:195], v[0:15]
	s_cbranch_scc1 .LBB0_756
.Lcnd1_rare:
	v_mov_b32_e32 v120, v168
	v_max_f32_e32 v120, v120, v120
	v_max_f32_e32 v121, v166, v166
	v_max_f32_e32 v165, v121, v120
	v_sub_f32_e32 v120, v166, v165
	v_mul_f32_e32 v120, 0x3e0293ee, v120
	v_exp_f32_e32 v120, v120
	s_and_saveexec_b64 s[56:57], s[4:5]
	ds_write_b32 v159, v120
	s_or_b64 exec, exec, s[56:57]
	s_waitcnt lgkmcnt(0)
	v_mul_f32_e32 v155, v155, v120
	ds_read_b128 v[120:123], v161
	ds_read_b128 v[124:127], v161 offset:32
	ds_read_b128 v[166:169], v161 offset:64
	ds_read_b128 v[170:173], v161 offset:96
	s_waitcnt lgkmcnt(0)
	v_pk_mul_f32 v[50:51], v[50:51], v[122:123]
	v_pk_mul_f32 v[54:55], v[54:55], v[126:127]
	v_pk_mul_f32 v[58:59], v[58:59], v[168:169]
	v_pk_mul_f32 v[62:63], v[62:63], v[172:173]
	v_pk_mul_f32 v[60:61], v[60:61], v[170:171]
	v_pk_mul_f32 v[56:57], v[56:57], v[166:167]
	v_pk_mul_f32 v[52:53], v[52:53], v[124:125]
	v_pk_mul_f32 v[48:49], v[48:49], v[120:121]
	v_pk_mul_f32 v[46:47], v[46:47], v[172:173]
	v_pk_mul_f32 v[42:43], v[42:43], v[168:169]
	v_pk_mul_f32 v[38:39], v[38:39], v[126:127]
	v_pk_mul_f32 v[34:35], v[34:35], v[122:123]
	v_pk_mul_f32 v[44:45], v[44:45], v[170:171]
	v_pk_mul_f32 v[40:41], v[40:41], v[166:167]
	v_pk_mul_f32 v[36:37], v[36:37], v[124:125]
	v_pk_mul_f32 v[32:33], v[32:33], v[120:121]
	v_pk_mul_f32 v[30:31], v[30:31], v[172:173]
	v_pk_mul_f32 v[26:27], v[26:27], v[168:169]
	v_pk_mul_f32 v[22:23], v[22:23], v[126:127]
	v_pk_mul_f32 v[18:19], v[18:19], v[122:123]
	v_pk_mul_f32 v[28:29], v[28:29], v[170:171]
	v_pk_mul_f32 v[24:25], v[24:25], v[166:167]
	v_pk_mul_f32 v[20:21], v[20:21], v[124:125]
	v_pk_mul_f32 v[16:17], v[16:17], v[120:121]
	v_pk_mul_f32 v[14:15], v[14:15], v[172:173]
	v_pk_mul_f32 v[10:11], v[10:11], v[168:169]
	v_pk_mul_f32 v[6:7], v[6:7], v[126:127]
	v_pk_mul_f32 v[2:3], v[2:3], v[122:123]
	v_pk_mul_f32 v[12:13], v[12:13], v[170:171]
	v_pk_mul_f32 v[8:9], v[8:9], v[166:167]
	v_pk_mul_f32 v[4:5], v[4:5], v[124:125]
	v_pk_mul_f32 v[0:1], v[0:1], v[120:121]
	s_andn2_b64 vcc, exec, s[54:55]
	s_cbranch_vccnz .LBB0_733
	s_branch .LBB0_757

.LBB0_911:
	s_or_b64 exec, exec, s[4:5]
	s_waitcnt lgkmcnt(0)
	s_barrier
	s_and_saveexec_b64 s[4:5], vcc
	s_cbranch_execz .LBB0_923
	s_ashr_i32 s55, s54, 31
	s_lshl_b64 s[2:3], s[54:55], 2
	s_add_u32 s2, s69, s2
	s_addc_u32 s3, s70, s3
	global_load_dword v2, v77, s[2:3]
	v_cmp_lt_i32_e32 vcc, -1, v78
	v_mov_b32_e32 v5, 0xff61b1e6
	s_and_saveexec_b64 s[6:7], vcc
	s_cbranch_execz .LBB0_922
	ds_read_b32 v5, v0
	v_lshlrev_b32_e32 v6, 2, v88
	ds_read_b32 v7, v6
	s_waitcnt lgkmcnt(0)
	s_nop 1
	v_max_f32_dpp v5, v5, v5 row_shr:1 row_mask:0xf bank_mask:0xf
	v_max_f32_dpp v7, v7, v7 row_shr:1 row_mask:0xf bank_mask:0xf
	s_nop 1
	v_max_f32_dpp v5, v5, v5 row_shr:2 row_mask:0xf bank_mask:0xf
	v_max_f32_dpp v7, v7, v7 row_shr:2 row_mask:0xf bank_mask:0xf
	s_nop 1
	v_max_f32_dpp v5, v5, v5 row_shr:4 row_mask:0xf bank_mask:0xf
	v_max_f32_dpp v7, v7, v7 row_shr:4 row_mask:0xf bank_mask:0xf
	s_nop 1
	v_max_f32_dpp v5, v5, v5 row_shr:8 row_mask:0xf bank_mask:0xf
	v_max_f32_dpp v7, v7, v7 row_shr:8 row_mask:0xf bank_mask:0xf
	s_nop 1
	v_max_f32_dpp v5, v5, v5 row_bcast:15 row_mask:0xa bank_mask:0xf
	v_max_f32_dpp v7, v7, v7 row_bcast:15 row_mask:0xa bank_mask:0xf
	s_nop 1
	v_max_f32_dpp v5, v5, v5 row_bcast:31 row_mask:0xc bank_mask:0xf
	v_max_f32_dpp v7, v7, v7 row_bcast:31 row_mask:0xc bank_mask:0xf
	s_nop 1
	v_readlane_b32 s8, v7, 63
	s_nop 3
	s_cmp_eq_u32 s71, 64
	s_cselect_b32 s8, s8, 0xff61b1e6
	v_max_f32_e32 v5, 0xff61b1e6, v5
	v_max_f32_e32 v5, s8, v5

.LBB0_923:
	s_or_b64 exec, exec, s[4:5]
	v_and_b32_e32 v92, 15, v88
	v_lshlrev_b32_e32 v76, 4, v92
	v_ashrrev_i32_e32 v64, 4, v78
	s_lshl_b32 s6, s16, 8
	s_add_u32 s4, s63, s6
	s_addc_u32 s5, s64, 0
	s_add_u32 s6, s65, s6
	s_addc_u32 s7, s66, 0
	v_add_u32_e32 v65, s91, v64
	v_lshl_add_u32 v65, v65, 10, v76
	s_ashr_i32 s55, s54, 31
	s_lshl_b64 s[8:9], s[54:55], 16
	s_add_u32 s8, s67, s8
	s_addc_u32 s9, s68, s9
	v_lshl_add_u32 v66, v64, 8, v76
	v_cmp_gt_i32_e64 s[2:3], s83, v78
	global_load_dwordx4 v[0:3], v65, s[4:5]
	global_load_dwordx4 v[4:7], v65, s[6:7]
	s_add_u32 s4, s4, 0x8000
	s_addc_u32 s5, s5, 0
	s_add_u32 s6, s6, 0x8000
	s_addc_u32 s7, s7, 0
	global_load_dwordx4 v[8:11], v65, s[4:5]
	global_load_dwordx4 v[12:15], v65, s[6:7]
	s_add_u32 s4, s4, 0x8000
	s_addc_u32 s5, s5, 0
	s_add_u32 s6, s6, 0x8000
	s_addc_u32 s7, s7, 0
	global_load_dwordx4 v[16:19], v65, s[4:5]
	global_load_dwordx4 v[20:23], v65, s[6:7]
	s_add_u32 s4, s4, 0x8000
	s_addc_u32 s5, s5, 0
	s_add_u32 s6, s6, 0x8000
	s_addc_u32 s7, s7, 0
	global_load_dwordx4 v[24:27], v65, s[4:5]
	global_load_dwordx4 v[28:31], v65, s[6:7]
	global_load_dwordx4 v[32:35], v66, s[8:9]
	s_add_u32 s8, s8, 0x2000
	s_addc_u32 s9, s9, 0
	global_load_dwordx4 v[36:39], v66, s[8:9]
	s_add_u32 s8, s8, 0x2000
	s_addc_u32 s9, s9, 0
	global_load_dwordx4 v[40:43], v66, s[8:9]
	s_add_u32 s8, s8, 0x2000
	s_addc_u32 s9, s9, 0
	global_load_dwordx4 v[44:47], v66, s[8:9]
	s_add_u32 s8, s8, 0x2000
	s_addc_u32 s9, s9, 0
	global_load_dwordx4 v[48:51], v66, s[8:9]
	s_add_u32 s8, s8, 0x2000
	s_addc_u32 s9, s9, 0
	global_load_dwordx4 v[52:55], v66, s[8:9]
	s_add_u32 s8, s8, 0x2000
	s_addc_u32 s9, s9, 0
	global_load_dwordx4 v[56:59], v66, s[8:9]
	s_add_u32 s8, s8, 0x2000
	s_addc_u32 s9, s9, 0
	global_load_dwordx4 v[60:63], v66, s[8:9]
	v_mad_u32_u24 v67, v64, s81, v76
	v_add_u32_e32 v68, s84, v67
	s_waitcnt vmcnt(15)
	ds_write_b128 v67, v[0:3] offset:4096
	s_waitcnt vmcnt(14)
	ds_write_b128 v67, v[4:7] offset:38912
	s_waitcnt vmcnt(13)
	ds_write_b128 v67, v[8:11] offset:12800
	s_waitcnt vmcnt(12)
	ds_write_b128 v67, v[12:15] offset:47616
	s_waitcnt vmcnt(11)
	ds_write_b128 v67, v[16:19] offset:21504
	s_waitcnt vmcnt(10)
	ds_write_b128 v67, v[20:23] offset:56320
	s_waitcnt vmcnt(9)
	ds_write_b128 v67, v[24:27] offset:30208
	s_waitcnt vmcnt(8)
	ds_write_b128 v67, v[28:31] offset:65024
	s_waitcnt vmcnt(7)
	ds_write_b128 v68, v[32:35] offset:0
	s_waitcnt vmcnt(6)
	ds_write_b128 v68, v[36:39] offset:8704
	s_waitcnt vmcnt(5)
	ds_write_b128 v68, v[40:43] offset:17408
	s_waitcnt vmcnt(4)
	ds_write_b128 v68, v[44:47] offset:26112
	s_waitcnt vmcnt(3)
	ds_write_b128 v68, v[48:51] offset:34816
	s_waitcnt vmcnt(2)
	ds_write_b128 v68, v[52:55] offset:43520
	s_waitcnt vmcnt(1)
	ds_write_b128 v68, v[56:59] offset:52224
	s_waitcnt vmcnt(0)
	ds_write_b128 v68, v[60:63] offset:60928
.LBB0_929:
	v_or_b32_e32 v1, s74, v92
	v_ashrrev_i32_e32 v58, 4, v88
	v_mad_u32_u24 v0, v1, s81, 0
	v_lshl_add_u32 v14, v58, 6, v0
	s_waitcnt lgkmcnt(0)
	s_barrier
	v_lshl_add_u32 v34, v58, 7, 0
	ds_read_b128 v[2:5], v14 offset:4096
	ds_read_b128 v[6:9], v14 offset:4112
	ds_read_b128 v[10:13], v14 offset:4128
	ds_read_b128 v[14:17], v14 offset:4144
	ds_read_b128 v[18:21], v34 offset:2560
	s_waitcnt lgkmcnt(4)
	v_lshlrev_b32_e32 v35, 16, v2
	v_and_b32_e32 v2, 0xffff0000, v2
	ds_read_b128 v[22:25], v34 offset:2576
	ds_read_b128 v[26:29], v34 offset:2592
	ds_read_b128 v[30:33], v34 offset:2608
	v_cmp_gt_u32_e32 vcc, 16, v88
	s_waitcnt lgkmcnt(3)
	v_fma_f32 v18, v18, v35, 0
	v_fmac_f32_e32 v18, v19, v2
	v_lshlrev_b32_e32 v2, 16, v3
	v_fmac_f32_e32 v18, v20, v2
	v_and_b32_e32 v2, 0xffff0000, v3
	v_fmac_f32_e32 v18, v21, v2
	v_lshlrev_b32_e32 v2, 16, v4
	s_waitcnt lgkmcnt(2)
	v_fmac_f32_e32 v18, v22, v2
	v_and_b32_e32 v2, 0xffff0000, v4
	v_fmac_f32_e32 v18, v23, v2
	v_lshlrev_b32_e32 v2, 16, v5
	v_fmac_f32_e32 v18, v24, v2
	v_and_b32_e32 v2, 0xffff0000, v5
	v_fmac_f32_e32 v18, v25, v2
	v_lshlrev_b32_e32 v2, 16, v6
	s_waitcnt lgkmcnt(1)
	v_fmac_f32_e32 v18, v26, v2
	v_and_b32_e32 v2, 0xffff0000, v6
	v_fmac_f32_e32 v18, v27, v2
	v_lshlrev_b32_e32 v2, 16, v7
	v_fmac_f32_e32 v18, v28, v2
	v_and_b32_e32 v2, 0xffff0000, v7
	v_fmac_f32_e32 v18, v29, v2
	v_lshlrev_b32_e32 v2, 16, v8
	s_waitcnt lgkmcnt(0)
	v_fmac_f32_e32 v18, v30, v2
	v_and_b32_e32 v2, 0xffff0000, v8
	v_fmac_f32_e32 v18, v31, v2
	v_lshlrev_b32_e32 v2, 16, v9
	v_fmac_f32_e32 v18, v32, v2
	ds_read_b128 v[2:5], v34 offset:2624
	v_and_b32_e32 v6, 0xffff0000, v9
	v_fmac_f32_e32 v18, v33, v6
	v_lshlrev_b32_e32 v19, 16, v10
	ds_read_b128 v[6:9], v34 offset:2640
	s_waitcnt lgkmcnt(1)
	v_fmac_f32_e32 v18, v2, v19
	v_and_b32_e32 v2, 0xffff0000, v10
	v_fmac_f32_e32 v18, v3, v2
	v_lshlrev_b32_e32 v2, 16, v11
	v_fmac_f32_e32 v18, v4, v2
	v_and_b32_e32 v2, 0xffff0000, v11
	v_fmac_f32_e32 v18, v5, v2
	v_lshlrev_b32_e32 v2, 16, v12
	s_waitcnt lgkmcnt(0)
	v_fmac_f32_e32 v18, v6, v2
	v_and_b32_e32 v2, 0xffff0000, v12
	v_fmac_f32_e32 v18, v7, v2
	v_lshlrev_b32_e32 v2, 16, v13
	v_fmac_f32_e32 v18, v8, v2
	ds_read_b128 v[2:5], v34 offset:2656
	v_and_b32_e32 v6, 0xffff0000, v13
	v_fmac_f32_e32 v18, v9, v6
	v_lshlrev_b32_e32 v10, 16, v14
	ds_read_b128 v[6:9], v34 offset:2672
	s_waitcnt lgkmcnt(1)
	v_fmac_f32_e32 v18, v2, v10
	v_and_b32_e32 v2, 0xffff0000, v14
	v_fmac_f32_e32 v18, v3, v2
	v_lshlrev_b32_e32 v2, 16, v15
	v_fmac_f32_e32 v18, v4, v2
	v_and_b32_e32 v2, 0xffff0000, v15
	v_fmac_f32_e32 v18, v5, v2
	v_lshlrev_b32_e32 v2, 16, v16
	s_waitcnt lgkmcnt(0)
	v_fmac_f32_e32 v18, v6, v2
	v_and_b32_e32 v2, 0xffff0000, v16
	v_fmac_f32_e32 v18, v7, v2
	v_lshlrev_b32_e32 v2, 16, v17
	v_fmac_f32_e32 v18, v8, v2
	v_and_b32_e32 v2, 0xffff0000, v17
	v_fmac_f32_e32 v18, v9, v2
	ds_bpermute_b32 v2, v80, v18
	s_waitcnt lgkmcnt(0)
	v_add_f32_e32 v2, v18, v2
	ds_bpermute_b32 v3, v81, v2
	s_and_saveexec_b64 s[4:5], vcc
	s_cbranch_execz .LBB0_931
	s_waitcnt lgkmcnt(0)
	v_add_f32_e32 v2, v2, v3
	v_lshl_add_u32 v1, v1, 2, 0
	ds_write_b32 v1, v2 offset:2048

.LBB0_946:
	v_add_u32_e32 v94, s75, v89
	v_lshl_add_u32 v76, v92, 2, 0
	ds_read_b128 v[48:51], v94 offset:512
	ds_read2_b32 v[56:57], v76 offset1:16
	v_add_u32_e32 v59, s84, v89
	v_add_u32_e32 v93, v59, v79
	ds_read_b128 v[52:55], v93
	v_lshl_add_u32 v91, v58, 2, s74
	s_waitcnt lgkmcnt(1)
	v_sub_f32_e32 v58, v56, v49
	v_mul_f32_e32 v58, 0x3fb8aa3b, v58
	v_exp_f32_e32 v58, v58
	v_sub_f32_e32 v60, v56, v48
	v_mul_f32_e32 v60, 0x3fb8aa3b, v60
	v_exp_f32_e32 v60, v60
	v_mul_f32_e32 v41, v41, v58
	v_sub_f32_e32 v58, v56, v50
	v_sub_f32_e32 v56, v56, v51
	v_mul_f32_e32 v56, 0x3fb8aa3b, v56
	v_exp_f32_e32 v56, v56
	v_mul_f32_e32 v58, 0x3fb8aa3b, v58
	v_exp_f32_e32 v58, v58
	v_mul_f32_e32 v40, v40, v60
	v_mul_f32_e32 v43, v43, v56
	v_sub_f32_e32 v56, v57, v48
	v_mul_f32_e32 v56, 0x3fb8aa3b, v56
	v_exp_f32_e32 v56, v56
	v_cmp_le_i32_e32 vcc, v92, v91
	v_or_b32_e32 v60, 1, v91
	v_or_b32_e32 v61, 2, v91
	v_mul_f32_e32 v28, v28, v56
	v_sub_f32_e32 v56, v57, v49
	v_mul_f32_e32 v56, 0x3fb8aa3b, v56
	v_cndmask_b32_e32 v134, 0, v40, vcc
	v_cmp_le_i32_e32 vcc, v92, v60
	v_exp_f32_e32 v56, v56
	v_mul_f32_e32 v42, v42, v58
	v_cndmask_b32_e32 v135, 0, v41, vcc
	v_cmp_le_i32_e32 vcc, v92, v61
	v_or_b32_e32 v58, 3, v91
	v_or_b32_e32 v62, 16, v92
	v_cndmask_b32_e32 v142, 0, v42, vcc
	v_cmp_le_i32_e32 vcc, v92, v58
	v_add_f32_e32 v42, 0, v142
	v_add_f32_e32 v40, 0, v134
	v_cndmask_b32_e32 v143, 0, v43, vcc
	v_cmp_le_i32_e32 vcc, v62, v91
	v_add_f32_e32 v43, 0, v143
	v_add_f32_e32 v41, 0, v135
	v_cndmask_b32_e32 v144, 0, v28, vcc
	v_mul_f32_e32 v28, v29, v56
	v_sub_f32_e32 v29, v57, v50
	v_mul_f32_e32 v29, 0x3fb8aa3b, v29
	v_exp_f32_e32 v29, v29
	v_cmp_le_i32_e32 vcc, v62, v60
	v_add_f32_e32 v40, v144, v40
	v_add_u32_e32 v95, 0x1100, v79
	v_cndmask_b32_e32 v145, 0, v28, vcc
	v_sub_f32_e32 v28, v57, v51
	v_mul_f32_e32 v28, 0x3fb8aa3b, v28
	v_mul_f32_e32 v30, v30, v29
	v_exp_f32_e32 v56, v28
	ds_read2_b32 v[28:29], v76 offset0:32 offset1:48
	v_cmp_le_i32_e32 vcc, v62, v61
	v_add_f32_e32 v41, v145, v41
	v_mul_f32_e32 v31, v31, v56
	v_cndmask_b32_e32 v146, 0, v30, vcc
	v_add_f32_e32 v30, v146, v42
	s_waitcnt lgkmcnt(0)
	v_sub_f32_e32 v42, v28, v48
	v_mul_f32_e32 v42, 0x3fb8aa3b, v42
	v_exp_f32_e32 v42, v42
	v_cmp_le_i32_e32 vcc, v62, v58
	v_add_u32_e32 v96, 0x2200, v79
	v_add_u32_e32 v97, 0x3300, v79
	v_cndmask_b32_e32 v147, 0, v31, vcc
	v_add_f32_e32 v31, v147, v43
	v_or_b32_e32 v43, 32, v92
	v_mul_f32_e32 v32, v32, v42
	v_cmp_le_i32_e32 vcc, v43, v91
	v_sub_f32_e32 v42, v28, v49
	v_mul_f32_e32 v42, 0x3fb8aa3b, v42
	v_cndmask_b32_e32 v148, 0, v32, vcc
	v_add_f32_e32 v32, v148, v40
	v_sub_f32_e32 v40, v28, v50
	v_exp_f32_e32 v42, v42
	v_mul_f32_e32 v40, 0x3fb8aa3b, v40
	v_exp_f32_e32 v40, v40
	v_cmp_le_i32_e32 vcc, v43, v60
	v_mul_f32_e32 v33, v33, v42
	v_sub_f32_e32 v28, v28, v51
	v_cndmask_b32_e32 v149, 0, v33, vcc
	v_mul_f32_e32 v34, v34, v40
	v_cmp_le_i32_e32 vcc, v43, v61
	v_mul_f32_e32 v28, 0x3fb8aa3b, v28
	v_exp_f32_e32 v28, v28
	v_cndmask_b32_e32 v150, 0, v34, vcc
	v_sub_f32_e32 v34, v29, v48
	v_mul_f32_e32 v34, 0x3fb8aa3b, v34
	v_exp_f32_e32 v34, v34
	v_mul_f32_e32 v28, v35, v28
	v_cmp_le_i32_e32 vcc, v43, v58
	v_add_f32_e32 v30, v150, v30
	v_mul_f32_e32 v16, v16, v34
	v_sub_f32_e32 v34, v29, v49
	v_mul_f32_e32 v34, 0x3fb8aa3b, v34
	v_exp_f32_e32 v34, v34
	v_cndmask_b32_e32 v151, 0, v28, vcc
	v_add_f32_e32 v28, v151, v31
	v_or_b32_e32 v31, 48, v92
	v_cmp_le_i32_e32 vcc, v31, v91
	v_add_f32_e32 v33, v149, v41
	v_add_u32_e32 v172, v59, v95
	v_cndmask_b32_e32 v152, 0, v16, vcc
	v_mul_f32_e32 v16, v17, v34
	v_sub_f32_e32 v17, v29, v50
	v_mul_f32_e32 v17, 0x3fb8aa3b, v17
	v_exp_f32_e32 v17, v17
	v_cmp_le_i32_e32 vcc, v31, v60
	v_add_f32_e32 v32, v152, v32
	v_add_u32_e32 v173, v59, v96
	v_cndmask_b32_e32 v153, 0, v16, vcc
	v_sub_f32_e32 v16, v29, v51
	v_mul_f32_e32 v16, 0x3fb8aa3b, v16
	v_mul_f32_e32 v18, v18, v17
	v_exp_f32_e32 v29, v16
	ds_read2_b32 v[16:17], v76 offset0:64 offset1:80
	v_cmp_le_i32_e32 vcc, v31, v61
	v_add_f32_e32 v33, v153, v33
	v_mul_f32_e32 v19, v19, v29
	v_cndmask_b32_e32 v154, 0, v18, vcc
	s_waitcnt lgkmcnt(0)
	v_sub_f32_e32 v29, v16, v48
	v_add_f32_e32 v18, v154, v30
	v_mul_f32_e32 v29, 0x3fb8aa3b, v29
	v_sub_f32_e32 v30, v16, v49
	v_exp_f32_e32 v29, v29
	v_cmp_le_i32_e32 vcc, v31, v58
	v_mul_f32_e32 v30, 0x3fb8aa3b, v30
	v_sub_f32_e32 v31, v16, v50
	v_exp_f32_e32 v30, v30
	v_mul_f32_e32 v31, 0x3fb8aa3b, v31
	v_cndmask_b32_e32 v155, 0, v19, vcc
	v_exp_f32_e32 v31, v31
	v_add_f32_e32 v19, v155, v28
	v_or_b32_e32 v28, 64, v92
	v_mul_f32_e32 v29, v36, v29
	v_cmp_le_i32_e32 vcc, v28, v91
	v_mul_f32_e32 v30, v37, v30
	v_mul_f32_e32 v31, v38, v31
	v_cndmask_b32_e32 v156, 0, v29, vcc
	v_cmp_le_i32_e32 vcc, v28, v60
	v_sub_f32_e32 v16, v16, v51
	v_mul_f32_e32 v16, 0x3fb8aa3b, v16
	v_cndmask_b32_e32 v157, 0, v30, vcc
	v_cmp_le_i32_e32 vcc, v28, v61
	v_exp_f32_e32 v16, v16
	v_add_f32_e32 v29, v156, v32
	v_cndmask_b32_e32 v158, 0, v31, vcc
	v_sub_f32_e32 v31, v17, v48
	v_mul_f32_e32 v31, 0x3fb8aa3b, v31
	v_exp_f32_e32 v31, v31
	v_mul_f32_e32 v16, v39, v16
	v_cmp_le_i32_e32 vcc, v28, v58
	v_or_b32_e32 v28, 0x50, v92
	v_add_f32_e32 v30, v157, v33
	v_cndmask_b32_e32 v159, 0, v16, vcc
	v_mul_f32_e32 v16, v20, v31
	v_sub_f32_e32 v20, v17, v49
	v_mul_f32_e32 v20, 0x3fb8aa3b, v20
	v_exp_f32_e32 v20, v20
	v_cmp_le_i32_e32 vcc, v28, v91
	v_add_f32_e32 v19, v159, v19
	v_add_f32_e32 v18, v158, v18
	v_cndmask_b32_e32 v160, 0, v16, vcc
	v_mul_f32_e32 v16, v21, v20
	v_sub_f32_e32 v20, v17, v50
	v_mul_f32_e32 v20, 0x3fb8aa3b, v20
	v_exp_f32_e32 v20, v20
	v_cmp_le_i32_e32 vcc, v28, v60
	v_add_f32_e32 v29, v160, v29
	v_add_u32_e32 v174, v59, v97
	v_cndmask_b32_e32 v161, 0, v16, vcc
	v_sub_f32_e32 v16, v17, v51
	v_mul_f32_e32 v16, 0x3fb8aa3b, v16
	v_mul_f32_e32 v20, v22, v20
	v_exp_f32_e32 v22, v16
	ds_read2_b32 v[16:17], v76 offset0:96 offset1:112
	v_cmp_le_i32_e32 vcc, v28, v61
	v_add_f32_e32 v21, v161, v30
	s_nop 0
	v_cndmask_b32_e32 v162, 0, v20, vcc
	v_mul_f32_e32 v20, v23, v22
	s_waitcnt lgkmcnt(0)
	v_sub_f32_e32 v22, v16, v48
	v_mul_f32_e32 v22, 0x3fb8aa3b, v22
	v_sub_f32_e32 v23, v16, v49
	v_exp_f32_e32 v22, v22
	v_cmp_le_i32_e32 vcc, v28, v58
	v_mul_f32_e32 v23, 0x3fb8aa3b, v23
	v_sub_f32_e32 v28, v16, v50
	v_exp_f32_e32 v23, v23
	v_mul_f32_e32 v28, 0x3fb8aa3b, v28
	v_exp_f32_e32 v28, v28
	v_cndmask_b32_e32 v163, 0, v20, vcc
	v_or_b32_e32 v20, 0x60, v92
	v_mul_f32_e32 v22, v44, v22
	v_cmp_le_i32_e32 vcc, v20, v91
	v_mul_f32_e32 v23, v45, v23
	v_sub_f32_e32 v16, v16, v51
	v_cndmask_b32_e32 v164, 0, v22, vcc
	v_cmp_le_i32_e32 vcc, v20, v60
	v_mul_f32_e32 v16, 0x3fb8aa3b, v16
	v_exp_f32_e32 v16, v16
	v_cndmask_b32_e32 v165, 0, v23, vcc
	v_mul_f32_e32 v23, v46, v28
	v_cmp_le_i32_e32 vcc, v20, v61
	v_mul_f32_e32 v16, v47, v16
	v_add_f32_e32 v19, v163, v19
	v_cndmask_b32_e32 v166, 0, v23, vcc
	v_sub_f32_e32 v23, v17, v48
	v_mul_f32_e32 v23, 0x3fb8aa3b, v23
	v_exp_f32_e32 v23, v23
	v_cmp_le_i32_e32 vcc, v20, v58
	v_add_f32_e32 v22, v164, v29
	v_add_f32_e32 v18, v162, v18
	v_mul_f32_e32 v20, v24, v23
	v_sub_f32_e32 v23, v17, v49
	v_mul_f32_e32 v23, 0x3fb8aa3b, v23
	v_cndmask_b32_e32 v167, 0, v16, vcc
	v_exp_f32_e32 v23, v23
	v_add_f32_e32 v16, v167, v19
	v_or_b32_e32 v19, 0x70, v92
	v_cmp_le_i32_e32 vcc, v19, v91
	v_add_f32_e32 v21, v165, v21
	v_add_f32_e32 v18, v166, v18
	v_cndmask_b32_e32 v168, 0, v20, vcc
	v_add_f32_e32 v20, v168, v22
	v_mul_f32_e32 v22, v25, v23
	v_sub_f32_e32 v23, v17, v50
	v_mul_f32_e32 v23, 0x3fb8aa3b, v23
	v_exp_f32_e32 v23, v23
	v_cmp_le_i32_e32 vcc, v19, v60
	v_sub_f32_e32 v17, v17, v51
	v_mul_f32_e32 v17, 0x3fb8aa3b, v17
	v_cndmask_b32_e32 v169, 0, v22, vcc
	v_mul_f32_e32 v22, v26, v23
	ds_bpermute_b32 v23, v82, v20
	v_cmp_le_i32_e32 vcc, v19, v61
	v_exp_f32_e32 v17, v17
	v_add_f32_e32 v21, v169, v21
	v_cndmask_b32_e32 v170, 0, v22, vcc
	s_waitcnt lgkmcnt(0)
	v_add_f32_e32 v20, v20, v23
	ds_bpermute_b32 v22, v83, v20
	v_add_f32_e32 v18, v170, v18
	v_mul_f32_e32 v17, v27, v17
	v_cmp_le_i32_e32 vcc, v19, v58
	ds_bpermute_b32 v19, v82, v18
	s_waitcnt lgkmcnt(1)
	v_add_f32_e32 v20, v20, v22
	ds_bpermute_b32 v22, v84, v20
	v_cndmask_b32_e32 v171, 0, v17, vcc
	ds_bpermute_b32 v17, v82, v21
	v_add_f32_e32 v16, v171, v16
	s_waitcnt lgkmcnt(2)
	v_add_f32_e32 v18, v18, v19
	s_waitcnt lgkmcnt(1)
	v_add_f32_e32 v102, v20, v22
	ds_bpermute_b32 v20, v82, v16
	s_waitcnt lgkmcnt(1)
	v_add_f32_e32 v17, v21, v17
	ds_bpermute_b32 v21, v83, v17
	ds_bpermute_b32 v19, v83, v18
	ds_read_b128 v[24:27], v173
	s_waitcnt lgkmcnt(3)
	v_add_f32_e32 v16, v16, v20
	ds_bpermute_b32 v20, v83, v16
	s_waitcnt lgkmcnt(3)
	v_add_f32_e32 v17, v17, v21
	s_waitcnt lgkmcnt(2)
	v_add_f32_e32 v18, v18, v19
	ds_bpermute_b32 v21, v84, v17
	ds_bpermute_b32 v19, v84, v18
	s_waitcnt lgkmcnt(2)
	v_add_f32_e32 v32, v16, v20
	ds_bpermute_b32 v33, v84, v32
	ds_read_b128 v[28:31], v174
	s_waitcnt lgkmcnt(3)
	v_add_f32_e32 v104, v17, v21
	s_waitcnt lgkmcnt(2)
	v_add_f32_e32 v106, v18, v19
	ds_read_b128 v[16:19], v172
	s_waitcnt lgkmcnt(2)
	v_add_f32_e32 v108, v32, v33
	ds_bpermute_b32 v103, v85, v102
	ds_bpermute_b32 v105, v85, v104
	ds_bpermute_b32 v107, v85, v106
	ds_bpermute_b32 v109, v85, v108
	v_mfma_f32_16x16x32_bf16 v[20:23], v[12:15], v[52:55], 0
	s_waitcnt lgkmcnt(4)
	v_mfma_f32_16x16x32_bf16 v[16:19], v[12:15], v[16:19], 0
	v_mfma_f32_16x16x32_bf16 v[24:27], v[12:15], v[24:27], 0
	v_mfma_f32_16x16x32_bf16 v[28:31], v[12:15], v[28:31], 0
	v_add_u32_e32 v98, 0x4400, v79
	v_add_u32_e32 v99, 0x5500, v79
	v_add_u32_e32 v100, 0x6600, v79
	v_add_u32_e32 v101, 0x7700, v79
	v_add_u32_e32 v175, v59, v98
	v_add_u32_e32 v176, v59, v99
	v_add_u32_e32 v177, v59, v100
	v_add_u32_e32 v178, v59, v101
	ds_read_b128 v[32:35], v175
	ds_read_b128 v[36:39], v176
	ds_read_b128 v[40:43], v177
	ds_read_b128 v[44:47], v178
	s_waitcnt lgkmcnt(3)
	v_mfma_f32_16x16x32_bf16 v[32:35], v[12:15], v[32:35], 0
	s_waitcnt lgkmcnt(2)
	v_mfma_f32_16x16x32_bf16 v[36:39], v[12:15], v[36:39], 0
	s_waitcnt lgkmcnt(1)
	v_mfma_f32_16x16x32_bf16 v[40:43], v[12:15], v[40:43], 0
	s_waitcnt lgkmcnt(0)
	v_mfma_f32_16x16x32_bf16 v[44:47], v[12:15], v[44:47], 0
	ds_read_b128 v[48:51], v93 offset:34816
	ds_read_b128 v[52:55], v93 offset:39168
	ds_read_b128 v[56:59], v93 offset:43520
	ds_read_b128 v[60:63], v93 offset:47872
	s_waitcnt lgkmcnt(3)
	v_mfma_f32_16x16x32_bf16 v[48:51], v[12:15], v[48:51], 0
	s_waitcnt lgkmcnt(2)
	v_mfma_f32_16x16x32_bf16 v[52:55], v[12:15], v[52:55], 0
	s_waitcnt lgkmcnt(1)
	v_mfma_f32_16x16x32_bf16 v[56:59], v[12:15], v[56:59], 0
	s_waitcnt lgkmcnt(0)
	v_mfma_f32_16x16x32_bf16 v[60:63], v[12:15], v[60:63], 0
	ds_read_b128 v[64:67], v93 offset:52224
	ds_read_b128 v[68:71], v93 offset:56576
	ds_read_b128 v[72:75], v93 offset:60928
	ds_read_b128 v[110:113], v93 offset:65280
	s_waitcnt lgkmcnt(3)
	v_mfma_f32_16x16x32_bf16 v[64:67], v[12:15], v[64:67], 0
	s_waitcnt lgkmcnt(2)
	v_mfma_f32_16x16x32_bf16 v[68:71], v[12:15], v[68:71], 0
	s_waitcnt lgkmcnt(1)
	v_mfma_f32_16x16x32_bf16 v[72:75], v[12:15], v[72:75], 0
	s_waitcnt lgkmcnt(0)
	v_mfma_f32_16x16x32_bf16 v[12:15], v[12:15], v[110:113], 0
	ds_read_b128 v[110:113], v93 offset:64
	ds_read_b128 v[114:117], v172 offset:64
	s_waitcnt lgkmcnt(1)
	v_mfma_f32_16x16x32_bf16 v[20:23], v[8:11], v[110:113], v[20:23]
	s_waitcnt lgkmcnt(0)
	v_mfma_f32_16x16x32_bf16 v[16:19], v[8:11], v[114:117], v[16:19]
	ds_read_b128 v[110:113], v173 offset:64
	ds_read_b128 v[114:117], v174 offset:64
	s_waitcnt lgkmcnt(1)
	v_mfma_f32_16x16x32_bf16 v[24:27], v[8:11], v[110:113], v[24:27]
	s_waitcnt lgkmcnt(0)
	v_mfma_f32_16x16x32_bf16 v[28:31], v[8:11], v[114:117], v[28:31]
	ds_read_b128 v[110:113], v175 offset:64
	ds_read_b128 v[114:117], v176 offset:64
	s_waitcnt lgkmcnt(1)
	v_mfma_f32_16x16x32_bf16 v[32:35], v[8:11], v[110:113], v[32:35]
	s_waitcnt lgkmcnt(0)
	v_mfma_f32_16x16x32_bf16 v[36:39], v[8:11], v[114:117], v[36:39]
	ds_read_b128 v[110:113], v177 offset:64
	ds_read_b128 v[114:117], v178 offset:64
	s_waitcnt lgkmcnt(1)
	v_mfma_f32_16x16x32_bf16 v[40:43], v[8:11], v[110:113], v[40:43]
	s_waitcnt lgkmcnt(0)
	v_mfma_f32_16x16x32_bf16 v[44:47], v[8:11], v[114:117], v[44:47]
	ds_read_b128 v[110:113], v93 offset:34880
	ds_read_b128 v[114:117], v93 offset:39232
	s_waitcnt lgkmcnt(1)
	v_mfma_f32_16x16x32_bf16 v[48:51], v[8:11], v[110:113], v[48:51]
	s_waitcnt lgkmcnt(0)
	v_mfma_f32_16x16x32_bf16 v[52:55], v[8:11], v[114:117], v[52:55]
	ds_read_b128 v[110:113], v93 offset:43584
	ds_read_b128 v[114:117], v93 offset:47936
	s_waitcnt lgkmcnt(1)
	v_mfma_f32_16x16x32_bf16 v[56:59], v[8:11], v[110:113], v[56:59]
	s_waitcnt lgkmcnt(0)
	v_mfma_f32_16x16x32_bf16 v[60:63], v[8:11], v[114:117], v[60:63]
	ds_read_b128 v[110:113], v93 offset:52288
	ds_read_b128 v[114:117], v93 offset:56640
	s_waitcnt lgkmcnt(1)
	v_mfma_f32_16x16x32_bf16 v[64:67], v[8:11], v[110:113], v[64:67]
	s_waitcnt lgkmcnt(0)
	v_mfma_f32_16x16x32_bf16 v[68:71], v[8:11], v[114:117], v[68:71]
	ds_read_b128 v[110:113], v93 offset:60992
	ds_read_b128 v[114:117], v93 offset:65344
	s_waitcnt lgkmcnt(1)
	v_mfma_f32_16x16x32_bf16 v[72:75], v[8:11], v[110:113], v[72:75]
	s_waitcnt lgkmcnt(0)
	v_mfma_f32_16x16x32_bf16 v[8:11], v[8:11], v[114:117], v[12:15]
	s_nop 2
	ds_read_b128 v[12:15], v93 offset:128
	ds_read_b128 v[110:113], v172 offset:128
	s_waitcnt lgkmcnt(1)
	v_mfma_f32_16x16x32_bf16 v[12:15], v[4:7], v[12:15], v[20:23]
	s_waitcnt lgkmcnt(0)
	v_mfma_f32_16x16x32_bf16 v[16:19], v[4:7], v[110:113], v[16:19]
	s_nop 0
	ds_read_b128 v[20:23], v173 offset:128
	ds_read_b128 v[110:113], v174 offset:128
	s_waitcnt lgkmcnt(1)
	v_mfma_f32_16x16x32_bf16 v[20:23], v[4:7], v[20:23], v[24:27]
	s_waitcnt lgkmcnt(0)
	v_mfma_f32_16x16x32_bf16 v[24:27], v[4:7], v[110:113], v[28:31]
	s_nop 2
	ds_read_b128 v[28:31], v175 offset:128
	ds_read_b128 v[110:113], v176 offset:128
	s_waitcnt lgkmcnt(1)
	v_mfma_f32_16x16x32_bf16 v[28:31], v[4:7], v[28:31], v[32:35]
	s_waitcnt lgkmcnt(0)
	v_mfma_f32_16x16x32_bf16 v[32:35], v[4:7], v[110:113], v[36:39]
	s_nop 2
	ds_read_b128 v[36:39], v177 offset:128
	ds_read_b128 v[110:113], v178 offset:128
	s_waitcnt lgkmcnt(1)
	v_mfma_f32_16x16x32_bf16 v[36:39], v[4:7], v[36:39], v[40:43]
	s_waitcnt lgkmcnt(0)
	v_mfma_f32_16x16x32_bf16 v[110:113], v[4:7], v[110:113], v[44:47]
	s_nop 0
	ds_read_b128 v[40:43], v93 offset:34944
	s_nop 0
	ds_read_b128 v[44:47], v93 offset:39296
	s_waitcnt lgkmcnt(1)
	v_mfma_f32_16x16x32_bf16 v[114:117], v[4:7], v[40:43], v[48:51]
	s_waitcnt lgkmcnt(0)
	v_mfma_f32_16x16x32_bf16 v[118:121], v[4:7], v[44:47], v[52:55]
	ds_read_b128 v[40:43], v93 offset:43648
	ds_read_b128 v[44:47], v93 offset:48000
	s_waitcnt lgkmcnt(1)
	v_mfma_f32_16x16x32_bf16 v[122:125], v[4:7], v[40:43], v[56:59]
	s_waitcnt lgkmcnt(0)
	v_mfma_f32_16x16x32_bf16 v[126:129], v[4:7], v[44:47], v[60:63]
	ds_read_b128 v[40:43], v93 offset:52352
	ds_read_b128 v[44:47], v93 offset:56704
	s_waitcnt lgkmcnt(1)
	v_mfma_f32_16x16x32_bf16 v[130:133], v[4:7], v[40:43], v[64:67]
	s_waitcnt lgkmcnt(0)
	v_mfma_f32_16x16x32_bf16 v[68:71], v[4:7], v[44:47], v[68:71]
	ds_read_b128 v[40:43], v93 offset:61056
	ds_read_b128 v[44:47], v93 offset:65408
	s_waitcnt lgkmcnt(1)
	v_mfma_f32_16x16x32_bf16 v[72:75], v[4:7], v[40:43], v[72:75]
	s_waitcnt lgkmcnt(0)
	v_mfma_f32_16x16x32_bf16 v[138:141], v[4:7], v[44:47], v[8:11]
	ds_read_b128 v[4:7], v93 offset:192
	s_nop 1
	ds_read_b128 v[8:11], v172 offset:192
	s_waitcnt lgkmcnt(1)
	v_mfma_f32_16x16x32_bf16 v[64:67], v[0:3], v[4:7], v[12:15]
	s_waitcnt lgkmcnt(0)
	v_mfma_f32_16x16x32_bf16 v[60:63], v[0:3], v[8:11], v[16:19]
	ds_read_b128 v[4:7], v173 offset:192
	ds_read_b128 v[8:11], v174 offset:192
	s_waitcnt lgkmcnt(1)
	v_mfma_f32_16x16x32_bf16 v[56:59], v[0:3], v[4:7], v[20:23]
	s_waitcnt lgkmcnt(0)
	v_mfma_f32_16x16x32_bf16 v[52:55], v[0:3], v[8:11], v[24:27]
	ds_read_b128 v[4:7], v175 offset:192
	ds_read_b128 v[8:11], v176 offset:192
	s_waitcnt lgkmcnt(1)
	v_mfma_f32_16x16x32_bf16 v[48:51], v[0:3], v[4:7], v[28:31]
	s_waitcnt lgkmcnt(0)
	v_mfma_f32_16x16x32_bf16 v[44:47], v[0:3], v[8:11], v[32:35]
	ds_read_b128 v[4:7], v177 offset:192
	ds_read_b128 v[8:11], v178 offset:192
	s_waitcnt lgkmcnt(1)
	v_mfma_f32_16x16x32_bf16 v[40:43], v[0:3], v[4:7], v[36:39]
	s_waitcnt lgkmcnt(0)
	v_mfma_f32_16x16x32_bf16 v[36:39], v[0:3], v[8:11], v[110:113]
	ds_read_b128 v[4:7], v93 offset:35008
	ds_read_b128 v[8:11], v93 offset:39360
	s_waitcnt lgkmcnt(1)
	v_mfma_f32_16x16x32_bf16 v[32:35], v[0:3], v[4:7], v[114:117]
	s_waitcnt lgkmcnt(0)
	v_mfma_f32_16x16x32_bf16 v[16:19], v[0:3], v[8:11], v[118:121]
	ds_read_b128 v[4:7], v93 offset:43712
	ds_read_b128 v[8:11], v93 offset:48064
	s_waitcnt lgkmcnt(1)
	v_mfma_f32_16x16x32_bf16 v[28:31], v[0:3], v[4:7], v[122:125]
	s_waitcnt lgkmcnt(0)
	v_mfma_f32_16x16x32_bf16 v[20:23], v[0:3], v[8:11], v[126:129]
	ds_read_b128 v[4:7], v93 offset:52416
	ds_read_b128 v[8:11], v93 offset:56768
	s_waitcnt lgkmcnt(1)
	v_mfma_f32_16x16x32_bf16 v[24:27], v[0:3], v[4:7], v[130:133]
	ds_read_b128 v[4:7], v93 offset:61120
	ds_read_b128 v[12:15], v93 offset:65472
	s_waitcnt lgkmcnt(2)
	v_mfma_f32_16x16x32_bf16 v[8:11], v[0:3], v[8:11], v[68:71]
	s_waitcnt lgkmcnt(1)
	v_mfma_f32_16x16x32_bf16 v[4:7], v[0:3], v[4:7], v[72:75]
	s_waitcnt lgkmcnt(0)
	v_mfma_f32_16x16x32_bf16 v[0:3], v[0:3], v[12:15], v[138:141]
	ds_read_b128 v[68:71], v94 offset:2048
	ds_read_b128 v[72:75], v94 offset:1536
	ds_read_b128 v[12:15], v94 offset:1024
	v_lshlrev_b32_e32 v92, 1, v92
	v_bfe_u32 v94, v134, 16, 1
	v_mul_lo_u32 v110, v91, s81
	v_add3_u32 v94, v134, v94, s87
	v_add3_u32 v92, 0, v92, v110
	s_waitcnt lgkmcnt(0)
	s_barrier
	ds_write_b16_d16_hi v92, v94 offset:38912
	v_bfe_u32 v94, v135, 16, 1
	v_add3_u32 v94, v135, v94, s87
	ds_write_b16_d16_hi v92, v94 offset:39184
	v_bfe_u32 v94, v142, 16, 1
	v_add3_u32 v94, v142, v94, s87
	ds_write_b16_d16_hi v92, v94 offset:39456
	v_bfe_u32 v94, v143, 16, 1
	v_add3_u32 v94, v143, v94, s87
	ds_write_b16_d16_hi v92, v94 offset:39728
	v_bfe_u32 v94, v144, 16, 1
	v_add3_u32 v94, v144, v94, s87
	ds_write_b16_d16_hi v92, v94 offset:38944
	v_bfe_u32 v94, v145, 16, 1
	v_add3_u32 v94, v145, v94, s87
	ds_write_b16_d16_hi v92, v94 offset:39216
	v_bfe_u32 v94, v146, 16, 1
	v_add3_u32 v94, v146, v94, s87
	ds_write_b16_d16_hi v92, v94 offset:39488
	v_bfe_u32 v94, v147, 16, 1
	v_add3_u32 v94, v147, v94, s87
	ds_write_b16_d16_hi v92, v94 offset:39760
	v_bfe_u32 v94, v148, 16, 1
	v_add3_u32 v94, v148, v94, s87
	ds_write_b16_d16_hi v92, v94 offset:38976
	v_bfe_u32 v94, v149, 16, 1
	v_add3_u32 v94, v149, v94, s87
	ds_write_b16_d16_hi v92, v94 offset:39248
	v_bfe_u32 v94, v150, 16, 1
	v_add3_u32 v94, v150, v94, s87
	ds_write_b16_d16_hi v92, v94 offset:39520
	v_bfe_u32 v94, v151, 16, 1
	v_add3_u32 v94, v151, v94, s87
	ds_write_b16_d16_hi v92, v94 offset:39792
	v_bfe_u32 v94, v152, 16, 1
	v_add3_u32 v94, v152, v94, s87
	ds_write_b16_d16_hi v92, v94 offset:39008
	v_bfe_u32 v94, v153, 16, 1
	v_add3_u32 v94, v153, v94, s87
	ds_write_b16_d16_hi v92, v94 offset:39280
	v_bfe_u32 v94, v154, 16, 1
	v_add3_u32 v94, v154, v94, s87
	ds_write_b16_d16_hi v92, v94 offset:39552
	v_bfe_u32 v94, v155, 16, 1
	v_add3_u32 v94, v155, v94, s87
	ds_write_b16_d16_hi v92, v94 offset:39824
	v_bfe_u32 v94, v156, 16, 1
	v_add3_u32 v94, v156, v94, s87
	ds_write_b16_d16_hi v92, v94 offset:39040
	v_bfe_u32 v94, v157, 16, 1
	v_add3_u32 v94, v157, v94, s87
	ds_write_b16_d16_hi v92, v94 offset:39312
	v_bfe_u32 v94, v158, 16, 1
	v_add3_u32 v94, v158, v94, s87
	ds_write_b16_d16_hi v92, v94 offset:39584
	v_bfe_u32 v94, v159, 16, 1
	v_add3_u32 v94, v159, v94, s87
	ds_write_b16_d16_hi v92, v94 offset:39856
	v_bfe_u32 v94, v160, 16, 1
	v_add3_u32 v94, v160, v94, s87
	ds_write_b16_d16_hi v92, v94 offset:39072
	v_bfe_u32 v94, v161, 16, 1
	v_add3_u32 v94, v161, v94, s87
	ds_write_b16_d16_hi v92, v94 offset:39344
	v_bfe_u32 v94, v162, 16, 1
	v_add3_u32 v94, v162, v94, s87
	ds_write_b16_d16_hi v92, v94 offset:39616
	v_bfe_u32 v94, v163, 16, 1
	v_add3_u32 v94, v163, v94, s87
	ds_write_b16_d16_hi v92, v94 offset:39888
	v_bfe_u32 v94, v164, 16, 1
	v_add3_u32 v94, v164, v94, s87
	ds_write_b16_d16_hi v92, v94 offset:39104
	v_bfe_u32 v94, v165, 16, 1
	v_add3_u32 v94, v165, v94, s87
	ds_write_b16_d16_hi v92, v94 offset:39376
	v_bfe_u32 v94, v166, 16, 1
	v_add3_u32 v94, v166, v94, s87
	ds_write_b16_d16_hi v92, v94 offset:39648
	v_bfe_u32 v94, v167, 16, 1
	v_add3_u32 v94, v167, v94, s87
	ds_write_b16_d16_hi v92, v94 offset:39920
	v_bfe_u32 v94, v168, 16, 1
	v_add3_u32 v94, v168, v94, s87
	ds_write_b16_d16_hi v92, v94 offset:39136
	v_bfe_u32 v94, v169, 16, 1
	v_add3_u32 v94, v169, v94, s87
	ds_write_b16_d16_hi v92, v94 offset:39408
	v_bfe_u32 v94, v170, 16, 1
	v_add3_u32 v94, v170, v94, s87
	ds_write_b16_d16_hi v92, v94 offset:39680
	v_bfe_u32 v94, v171, 16, 1
	v_add3_u32 v94, v171, v94, s87
	ds_write_b16_d16_hi v92, v94 offset:39952
	s_and_saveexec_b64 s[4:5], s[2:3]
	s_cbranch_execz .LBB0_949
	s_lshl_b32 s6, s16, 9
	s_add_u32 s6, s30, s6
	s_addc_u32 s7, s31, 0
	v_and_b32_e32 v212, 0x7f, v78
	v_ashrrev_i32_e32 v213, 7, v78
	v_or_b32_e32 v214, s91, v212
	v_mul_lo_u32 v214, v214, s88
	v_lshl_add_u32 v214, v213, 4, v214
	global_load_dwordx4 v[180:183], v214, s[6:7] offset:2048
	global_load_dwordx4 v[184:187], v214, s[6:7] offset:2112
	global_load_dwordx4 v[188:191], v214, s[6:7] offset:2176
	global_load_dwordx4 v[192:195], v214, s[6:7] offset:2240
	global_load_dwordx4 v[196:199], v214, s[6:7] offset:2304
	global_load_dwordx4 v[200:203], v214, s[6:7] offset:2368
	global_load_dwordx4 v[204:207], v214, s[6:7] offset:2432
	global_load_dwordx4 v[208:211], v214, s[6:7] offset:2496
	v_mul_u32_u24_e32 v215, 0x880, v213
	v_lshl_add_u32 v215, v212, 1, v215
	v_add_u32_e32 v215, s84, v215
	s_waitcnt vmcnt(7)
	ds_write_b16 v215, v180 offset:0
	ds_write_b16_d16_hi v215, v180 offset:272
	ds_write_b16 v215, v181 offset:544
	ds_write_b16_d16_hi v215, v181 offset:816
	ds_write_b16 v215, v182 offset:1088
	ds_write_b16_d16_hi v215, v182 offset:1360
	ds_write_b16 v215, v183 offset:1632
	ds_write_b16_d16_hi v215, v183 offset:1904
	s_waitcnt vmcnt(6)
	ds_write_b16 v215, v184 offset:8704
	ds_write_b16_d16_hi v215, v184 offset:8976
	ds_write_b16 v215, v185 offset:9248
	ds_write_b16_d16_hi v215, v185 offset:9520
	ds_write_b16 v215, v186 offset:9792
	ds_write_b16_d16_hi v215, v186 offset:10064
	ds_write_b16 v215, v187 offset:10336
	ds_write_b16_d16_hi v215, v187 offset:10608
	s_waitcnt vmcnt(5)
	ds_write_b16 v215, v188 offset:17408
	ds_write_b16_d16_hi v215, v188 offset:17680
	ds_write_b16 v215, v189 offset:17952
	ds_write_b16_d16_hi v215, v189 offset:18224
	ds_write_b16 v215, v190 offset:18496
	ds_write_b16_d16_hi v215, v190 offset:18768
	ds_write_b16 v215, v191 offset:19040
	ds_write_b16_d16_hi v215, v191 offset:19312
	s_waitcnt vmcnt(4)
	ds_write_b16 v215, v192 offset:26112
	ds_write_b16_d16_hi v215, v192 offset:26384
	ds_write_b16 v215, v193 offset:26656
	ds_write_b16_d16_hi v215, v193 offset:26928
	ds_write_b16 v215, v194 offset:27200
	ds_write_b16_d16_hi v215, v194 offset:27472
	ds_write_b16 v215, v195 offset:27744
	ds_write_b16_d16_hi v215, v195 offset:28016
	s_waitcnt vmcnt(3)
	ds_write_b16 v215, v196 offset:34816
	ds_write_b16_d16_hi v215, v196 offset:35088
	ds_write_b16 v215, v197 offset:35360
	ds_write_b16_d16_hi v215, v197 offset:35632
	ds_write_b16 v215, v198 offset:35904
	ds_write_b16_d16_hi v215, v198 offset:36176
	ds_write_b16 v215, v199 offset:36448
	ds_write_b16_d16_hi v215, v199 offset:36720
	s_waitcnt vmcnt(2)
	ds_write_b16 v215, v200 offset:43520
	ds_write_b16_d16_hi v215, v200 offset:43792
	ds_write_b16 v215, v201 offset:44064
	ds_write_b16_d16_hi v215, v201 offset:44336
	ds_write_b16 v215, v202 offset:44608
	ds_write_b16_d16_hi v215, v202 offset:44880
	ds_write_b16 v215, v203 offset:45152
	ds_write_b16_d16_hi v215, v203 offset:45424
	s_waitcnt vmcnt(1)
	ds_write_b16 v215, v204 offset:52224
	ds_write_b16_d16_hi v215, v204 offset:52496
	ds_write_b16 v215, v205 offset:52768
	ds_write_b16_d16_hi v215, v205 offset:53040
	ds_write_b16 v215, v206 offset:53312
	ds_write_b16_d16_hi v215, v206 offset:53584
	ds_write_b16 v215, v207 offset:53856
	ds_write_b16_d16_hi v215, v207 offset:54128
	s_waitcnt vmcnt(0)
	ds_write_b16 v215, v208 offset:60928
	ds_write_b16_d16_hi v215, v208 offset:61200
	ds_write_b16 v215, v209 offset:61472
	ds_write_b16_d16_hi v215, v209 offset:61744
	ds_write_b16 v215, v210 offset:62016
	ds_write_b16_d16_hi v215, v210 offset:62288
	ds_write_b16 v215, v211 offset:62560
	ds_write_b16_d16_hi v215, v211 offset:62832
